# prologue: nt hint on the fp8 expert-weight stores (not re-read for many phases) so they do not displace data the next phase reads
# speedup vs baseline: 1.0158x; 1.0158x over previous
.LBB0_457:
	s_sext_i32_i16 s12, s41
	v_cvt_f32_i32_e32 v4, s12
	s_xor_b64 s[36:37], s[22:23], -1
	s_sext_i32_i16 s22, s40
	v_cvt_f32_i32_e32 v5, s22
	v_rcp_iflag_f32_e32 v6, v4
	s_xor_b32 s12, s22, s12
	s_ashr_i32 s12, s12, 30
	s_or_b32 s12, s12, 1
	v_mul_f32_e32 v6, v5, v6
	v_trunc_f32_e32 v6, v6
	v_fma_f32 v5, -v6, v4, v5
	v_cvt_i32_f32_e32 v6, v6
	v_cmp_ge_f32_e64 s[22:23], |v5|, |v4|
	s_and_b64 s[22:23], s[22:23], exec
	s_cselect_b32 s12, s12, 0
	v_readfirstlane_b32 s22, v6
	s_add_i32 s22, s22, s12
	s_sext_i32_i16 s12, s22
	s_mul_i32 s23, s22, s41
	s_sub_i32 s23, s40, s23
	s_ashr_i32 s26, s12, 1
	s_sext_i32_i16 s38, s23
	s_ashr_i32 s27, s26, 31
	s_lshl_b32 s23, s22, 6
	s_lshl_b32 s41, s38, 6
	s_and_b32 s40, s38, -16
	s_lshl_b64 s[26:27], s[26:27], 15
	s_add_u32 s26, s0, s26
	s_addc_u32 s27, s1, s27
	s_and_b32 s12, s23, 64
	s_bfe_i64 s[22:23], s[22:23], 0x100000
	s_lshl_b64 s[22:23], s[22:23], 15
	s_add_u32 s22, s0, s22
	s_addc_u32 s23, s1, s23
	s_lshl_b32 s0, s38, 7
	s_and_b32 s38, s0, 0x780
	s_waitcnt lgkmcnt(14)
	v_or_b32_e32 v90, s40, v35
	ds_read_b32 v91, v36
	v_or_b32_e32 v4, s41, v35
	v_add_u32_e32 v5, s38, v90
	v_cndmask_b32_e64 v6, v4, v5, s[16:17]
	v_ashrrev_i32_e32 v4, 8, v6
	v_and_b32_e32 v6, 0xf7, v6
	v_ashrrev_i32_e32 v5, 31, v4
	s_mov_b64 s[0:1], -1
	s_and_b64 vcc, exec, s[36:37]
	v_add_u32_e32 v89, 0x200, v36
	v_add_u32_e32 v88, 0x400, v36
	v_lshlrev_b32_e32 v6, 7, v6
	s_cbranch_vccz .LBB0_459
	ds_read2_b32 v[92:93], v36 offset0:65 offset1:130
	ds_read2_b32 v[94:95], v89 offset0:67 offset1:132
	ds_read2_b32 v[96:97], v88 offset0:69 offset1:134
	s_waitcnt lgkmcnt(3)
	v_mul_f32_e32 v7, 0x42800000, v91
	s_mov_b64 s[0:1], 0
	s_waitcnt lgkmcnt(2)
	v_mul_f32_e32 v98, 0x42800000, v92
	v_mov_b32_e32 v92, v33
	v_cvt_pk_fp8_f32 v92, v7, v98
	s_waitcnt lgkmcnt(1)
	v_mul_f32_e32 v7, 0x42800000, v95
	s_waitcnt lgkmcnt(0)
	v_mul_f32_e32 v95, 0x42800000, v96
	ds_read_b32 v96, v36 offset:1820
	v_mul_f32_e32 v99, 0x42800000, v93
	v_mov_b32_e32 v93, v33
	v_cvt_pk_fp8_f32 v93, v7, v95
	v_mul_f32_e32 v94, 0x42800000, v94
	v_cvt_pk_fp8_f32 v92, v99, v94 op_sel:[0,0,1]
	v_mul_f32_e32 v7, 0x42800000, v97
	s_waitcnt lgkmcnt(0)
	v_mul_f32_e32 v94, 0x42800000, v96
	v_cvt_pk_fp8_f32 v93, v7, v94 op_sel:[0,0,1]
	v_lshlrev_b64 v[94:95], 18, v[4:5]
	v_lshl_add_u64 v[94:95], s[26:27], 0, v[94:95]
	v_mov_b32_e32 v7, v33
	v_lshl_add_u64 v[94:95], v[94:95], 0, v[6:7]
	v_lshl_add_u64 v[94:95], v[94:95], 0, s[12:13]
	v_lshl_add_u64 v[94:95], v[94:95], 0, v[0:1]
	global_store_dwordx2 v[94:95], v[92:93], off nt

.LBB0_461:
	v_or_b32_e32 v5, s40, v37
	s_waitcnt lgkmcnt(0)
	ds_read_b32 v91, v36 offset:32
	v_or_b32_e32 v4, s41, v37
	v_add_u32_e32 v5, s38, v5
	v_cndmask_b32_e64 v6, v4, v5, s[16:17]
	v_ashrrev_i32_e32 v4, 8, v6
	v_cndmask_b32_e64 v7, 0, 1, s[36:37]
	v_ashrrev_i32_e32 v5, 31, v4
	s_mov_b64 s[38:39], -1
	v_cmp_ne_u32_e64 s[0:1], 1, v7
	s_andn2_b64 vcc, exec, s[36:37]
	v_lshlrev_b32_sdwa v6, v211, v6 dst_sel:DWORD dst_unused:UNUSED_PAD src0_sel:DWORD src1_sel:BYTE_0
	s_cbranch_vccnz .LBB0_463
	ds_read2_b32 v[92:93], v36 offset0:73 offset1:138
	ds_read2_b32 v[94:95], v89 offset0:75 offset1:140
	ds_read2_b32 v[96:97], v88 offset0:77 offset1:142
	s_waitcnt lgkmcnt(3)
	v_mul_f32_e32 v7, 0x42800000, v91
	s_mov_b64 s[38:39], 0
	s_waitcnt lgkmcnt(2)
	v_mul_f32_e32 v98, 0x42800000, v92
	v_mov_b32_e32 v92, v33
	v_cvt_pk_fp8_f32 v92, v7, v98
	s_waitcnt lgkmcnt(1)
	v_mul_f32_e32 v7, 0x42800000, v95
	s_waitcnt lgkmcnt(0)
	v_mul_f32_e32 v95, 0x42800000, v96
	ds_read_b32 v96, v36 offset:1852
	v_mul_f32_e32 v99, 0x42800000, v93
	v_mov_b32_e32 v93, v33
	v_cvt_pk_fp8_f32 v93, v7, v95
	v_mul_f32_e32 v94, 0x42800000, v94
	v_cvt_pk_fp8_f32 v92, v99, v94 op_sel:[0,0,1]
	v_mul_f32_e32 v7, 0x42800000, v97
	s_waitcnt lgkmcnt(0)
	v_mul_f32_e32 v94, 0x42800000, v96
	v_cvt_pk_fp8_f32 v93, v7, v94 op_sel:[0,0,1]
	v_lshlrev_b64 v[94:95], 18, v[4:5]
	v_lshl_add_u64 v[94:95], s[26:27], 0, v[94:95]
	v_mov_b32_e32 v7, v33
	v_lshl_add_u64 v[94:95], v[94:95], 0, v[6:7]
	v_lshl_add_u64 v[94:95], v[94:95], 0, s[12:13]
	v_lshl_add_u64 v[94:95], v[94:95], 0, v[0:1]
	global_store_dwordx2 v[94:95], v[92:93], off nt

.LBB0_465:
	v_or_b32_e32 v4, s41, v39
	v_lshlrev_b32_e32 v5, 1, v4
	v_and_b32_e32 v5, 0x7a0, v5
	s_waitcnt lgkmcnt(0)
	ds_read_b32 v91, v36 offset:64
	v_add_u32_e32 v5, v5, v90
	v_cndmask_b32_e64 v6, v4, v5, s[16:17]
	v_ashrrev_i32_e32 v4, 8, v6
	v_and_b32_e32 v6, 0xf7, v6
	v_ashrrev_i32_e32 v5, 31, v4
	s_mov_b64 s[36:37], -1
	s_and_b64 vcc, exec, s[0:1]
	v_lshlrev_b32_e32 v6, 7, v6
	s_cbranch_vccnz .LBB0_467
	ds_read2_b32 v[92:93], v36 offset0:81 offset1:146
	ds_read2_b32 v[94:95], v89 offset0:83 offset1:148
	ds_read2_b32 v[96:97], v88 offset0:85 offset1:150
	s_waitcnt lgkmcnt(3)
	v_mul_f32_e32 v7, 0x42800000, v91
	s_mov_b64 s[36:37], 0
	s_waitcnt lgkmcnt(2)
	v_mul_f32_e32 v98, 0x42800000, v92
	v_mov_b32_e32 v92, v33
	v_cvt_pk_fp8_f32 v92, v7, v98
	s_waitcnt lgkmcnt(1)
	v_mul_f32_e32 v7, 0x42800000, v95
	s_waitcnt lgkmcnt(0)
	v_mul_f32_e32 v95, 0x42800000, v96
	ds_read_b32 v96, v36 offset:1884
	v_mul_f32_e32 v99, 0x42800000, v93
	v_mov_b32_e32 v93, v33
	v_cvt_pk_fp8_f32 v93, v7, v95
	v_mul_f32_e32 v94, 0x42800000, v94
	v_cvt_pk_fp8_f32 v92, v99, v94 op_sel:[0,0,1]
	v_mul_f32_e32 v7, 0x42800000, v97
	s_waitcnt lgkmcnt(0)
	v_mul_f32_e32 v94, 0x42800000, v96
	v_cvt_pk_fp8_f32 v93, v7, v94 op_sel:[0,0,1]
	v_lshlrev_b64 v[94:95], 18, v[4:5]
	v_lshl_add_u64 v[94:95], s[26:27], 0, v[94:95]
	v_mov_b32_e32 v7, v33
	v_lshl_add_u64 v[94:95], v[94:95], 0, v[6:7]
	v_lshl_add_u64 v[94:95], v[94:95], 0, s[12:13]
	v_lshl_add_u64 v[94:95], v[94:95], 0, v[0:1]
	global_store_dwordx2 v[94:95], v[92:93], off nt

.LBB0_469:
	v_or_b32_e32 v4, s41, v40
	v_lshlrev_b32_e32 v5, 1, v4
	v_and_b32_e32 v5, 0x7a0, v5
	v_or_b32_e32 v6, s40, v41
	s_waitcnt lgkmcnt(0)
	ds_read_b32 v91, v36 offset:96
	v_add_u32_e32 v5, v6, v5
	v_cndmask_b32_e64 v6, v4, v5, s[16:17]
	v_ashrrev_i32_e32 v4, 8, v6
	v_ashrrev_i32_e32 v5, 31, v4
	s_mov_b64 s[36:37], -1
	s_and_b64 vcc, exec, s[0:1]
	v_lshlrev_b32_sdwa v6, v211, v6 dst_sel:DWORD dst_unused:UNUSED_PAD src0_sel:DWORD src1_sel:BYTE_0
	s_cbranch_vccnz .LBB0_471
	ds_read2_b32 v[92:93], v36 offset0:89 offset1:154
	ds_read2_b32 v[94:95], v89 offset0:91 offset1:156
	ds_read2_b32 v[96:97], v88 offset0:93 offset1:158
	s_waitcnt lgkmcnt(3)
	v_mul_f32_e32 v7, 0x42800000, v91
	s_mov_b64 s[36:37], 0
	s_waitcnt lgkmcnt(2)
	v_mul_f32_e32 v98, 0x42800000, v92
	v_mov_b32_e32 v92, v33
	v_cvt_pk_fp8_f32 v92, v7, v98
	s_waitcnt lgkmcnt(1)
	v_mul_f32_e32 v7, 0x42800000, v95
	s_waitcnt lgkmcnt(0)
	v_mul_f32_e32 v95, 0x42800000, v96
	ds_read_b32 v96, v36 offset:1916
	v_mul_f32_e32 v99, 0x42800000, v93
	v_mov_b32_e32 v93, v33
	v_cvt_pk_fp8_f32 v93, v7, v95
	v_mul_f32_e32 v94, 0x42800000, v94
	v_cvt_pk_fp8_f32 v92, v99, v94 op_sel:[0,0,1]
	v_mul_f32_e32 v7, 0x42800000, v97
	s_waitcnt lgkmcnt(0)
	v_mul_f32_e32 v94, 0x42800000, v96
	v_cvt_pk_fp8_f32 v93, v7, v94 op_sel:[0,0,1]
	v_lshlrev_b64 v[94:95], 18, v[4:5]
	v_lshl_add_u64 v[94:95], s[26:27], 0, v[94:95]
	v_mov_b32_e32 v7, v33
	v_lshl_add_u64 v[94:95], v[94:95], 0, v[6:7]
	v_lshl_add_u64 v[94:95], v[94:95], 0, s[12:13]
	v_lshl_add_u64 v[94:95], v[94:95], 0, v[0:1]
	global_store_dwordx2 v[94:95], v[92:93], off nt

.LBB0_473:
	v_or_b32_e32 v4, s41, v42
	v_lshlrev_b32_e32 v5, 1, v4
	v_and_b32_e32 v5, 0x7c0, v5
	s_waitcnt lgkmcnt(0)
	ds_read_b32 v91, v36 offset:128
	v_add_u32_e32 v5, v5, v90
	v_cndmask_b32_e64 v6, v4, v5, s[16:17]
	v_ashrrev_i32_e32 v4, 8, v6
	v_and_b32_e32 v6, 0xf7, v6
	v_ashrrev_i32_e32 v5, 31, v4
	s_mov_b64 s[36:37], -1
	s_and_b64 vcc, exec, s[0:1]
	v_lshlrev_b32_e32 v6, 7, v6
	s_cbranch_vccnz .LBB0_475
	ds_read2_b32 v[92:93], v36 offset0:97 offset1:162
	ds_read2_b32 v[94:95], v89 offset0:99 offset1:164
	ds_read2_b32 v[96:97], v88 offset0:101 offset1:166
	s_waitcnt lgkmcnt(3)
	v_mul_f32_e32 v7, 0x42800000, v91
	s_mov_b64 s[36:37], 0
	s_waitcnt lgkmcnt(2)
	v_mul_f32_e32 v98, 0x42800000, v92
	v_mov_b32_e32 v92, v33
	v_cvt_pk_fp8_f32 v92, v7, v98
	s_waitcnt lgkmcnt(1)
	v_mul_f32_e32 v7, 0x42800000, v95
	s_waitcnt lgkmcnt(0)
	v_mul_f32_e32 v95, 0x42800000, v96
	ds_read_b32 v96, v36 offset:1948
	v_mul_f32_e32 v99, 0x42800000, v93
	v_mov_b32_e32 v93, v33
	v_cvt_pk_fp8_f32 v93, v7, v95
	v_mul_f32_e32 v94, 0x42800000, v94
	v_cvt_pk_fp8_f32 v92, v99, v94 op_sel:[0,0,1]
	v_mul_f32_e32 v7, 0x42800000, v97
	s_waitcnt lgkmcnt(0)
	v_mul_f32_e32 v94, 0x42800000, v96
	v_cvt_pk_fp8_f32 v93, v7, v94 op_sel:[0,0,1]
	v_lshlrev_b64 v[94:95], 18, v[4:5]
	v_lshl_add_u64 v[94:95], s[26:27], 0, v[94:95]
	v_mov_b32_e32 v7, v33
	v_lshl_add_u64 v[94:95], v[94:95], 0, v[6:7]
	v_lshl_add_u64 v[94:95], v[94:95], 0, s[12:13]
	v_lshl_add_u64 v[94:95], v[94:95], 0, v[0:1]
	global_store_dwordx2 v[94:95], v[92:93], off nt

.LBB0_477:
	v_or_b32_e32 v4, s41, v43
	v_lshlrev_b32_e32 v5, 1, v4
	v_and_b32_e32 v5, 0x7c0, v5
	v_or_b32_e32 v6, s40, v44
	s_waitcnt lgkmcnt(0)
	ds_read_b32 v91, v36 offset:160
	v_add_u32_e32 v5, v6, v5
	v_cndmask_b32_e64 v6, v4, v5, s[16:17]
	v_ashrrev_i32_e32 v4, 8, v6
	v_ashrrev_i32_e32 v5, 31, v4
	s_mov_b64 s[36:37], -1
	s_and_b64 vcc, exec, s[0:1]
	v_lshlrev_b32_sdwa v6, v211, v6 dst_sel:DWORD dst_unused:UNUSED_PAD src0_sel:DWORD src1_sel:BYTE_0
	s_cbranch_vccnz .LBB0_479
	ds_read2_b32 v[92:93], v36 offset0:105 offset1:170
	ds_read2_b32 v[94:95], v89 offset0:107 offset1:172
	ds_read2_b32 v[96:97], v88 offset0:109 offset1:174
	s_waitcnt lgkmcnt(3)
	v_mul_f32_e32 v7, 0x42800000, v91
	s_mov_b64 s[36:37], 0
	s_waitcnt lgkmcnt(2)
	v_mul_f32_e32 v98, 0x42800000, v92
	v_mov_b32_e32 v92, v33
	v_cvt_pk_fp8_f32 v92, v7, v98
	s_waitcnt lgkmcnt(1)
	v_mul_f32_e32 v7, 0x42800000, v95
	s_waitcnt lgkmcnt(0)
	v_mul_f32_e32 v95, 0x42800000, v96
	ds_read_b32 v96, v36 offset:1980
	v_mul_f32_e32 v99, 0x42800000, v93
	v_mov_b32_e32 v93, v33
	v_cvt_pk_fp8_f32 v93, v7, v95
	v_mul_f32_e32 v94, 0x42800000, v94
	v_cvt_pk_fp8_f32 v92, v99, v94 op_sel:[0,0,1]
	v_mul_f32_e32 v7, 0x42800000, v97
	s_waitcnt lgkmcnt(0)
	v_mul_f32_e32 v94, 0x42800000, v96
	v_cvt_pk_fp8_f32 v93, v7, v94 op_sel:[0,0,1]
	v_lshlrev_b64 v[94:95], 18, v[4:5]
	v_lshl_add_u64 v[94:95], s[26:27], 0, v[94:95]
	v_mov_b32_e32 v7, v33
	v_lshl_add_u64 v[94:95], v[94:95], 0, v[6:7]
	v_lshl_add_u64 v[94:95], v[94:95], 0, s[12:13]
	v_lshl_add_u64 v[94:95], v[94:95], 0, v[0:1]
	global_store_dwordx2 v[94:95], v[92:93], off nt

.LBB0_481:
	v_or_b32_e32 v4, s41, v45
	v_lshlrev_b32_e32 v5, 1, v4
	v_and_b32_e32 v5, 0x7e0, v5
	v_add_u32_e32 v5, v5, v90
	ds_read_b32 v90, v36 offset:192
	v_cndmask_b32_e64 v6, v4, v5, s[16:17]
	v_ashrrev_i32_e32 v4, 8, v6
	v_and_b32_e32 v6, 0xf7, v6
	v_ashrrev_i32_e32 v5, 31, v4
	s_mov_b64 s[36:37], -1
	s_and_b64 vcc, exec, s[0:1]
	v_lshlrev_b32_e32 v6, 7, v6
	s_cbranch_vccnz .LBB0_483
	ds_read2_b32 v[92:93], v36 offset0:113 offset1:178
	ds_read2_b32 v[94:95], v89 offset0:115 offset1:180
	ds_read2_b32 v[96:97], v88 offset0:117 offset1:182
	s_waitcnt lgkmcnt(3)
	v_mul_f32_e32 v7, 0x42800000, v90
	s_mov_b64 s[36:37], 0
	s_waitcnt lgkmcnt(2)
	v_mul_f32_e32 v91, 0x42800000, v92
	v_mov_b32_e32 v92, v33
	v_cvt_pk_fp8_f32 v92, v7, v91
	s_waitcnt lgkmcnt(1)
	v_mul_f32_e32 v7, 0x42800000, v95
	ds_read_b32 v95, v36 offset:2012
	v_mul_f32_e32 v98, 0x42800000, v93
	s_waitcnt lgkmcnt(1)
	v_mul_f32_e32 v91, 0x42800000, v96
	v_mov_b32_e32 v93, v33
	v_cvt_pk_fp8_f32 v93, v7, v91
	v_mul_f32_e32 v94, 0x42800000, v94
	v_cvt_pk_fp8_f32 v92, v98, v94 op_sel:[0,0,1]
	v_mul_f32_e32 v7, 0x42800000, v97
	s_waitcnt lgkmcnt(0)
	v_mul_f32_e32 v91, 0x42800000, v95
	v_lshlrev_b64 v[94:95], 18, v[4:5]
	v_cvt_pk_fp8_f32 v93, v7, v91 op_sel:[0,0,1]
	v_lshl_add_u64 v[94:95], s[26:27], 0, v[94:95]
	v_mov_b32_e32 v7, v33
	v_lshl_add_u64 v[94:95], v[94:95], 0, v[6:7]
	v_lshl_add_u64 v[94:95], v[94:95], 0, s[12:13]
	v_lshl_add_u64 v[94:95], v[94:95], 0, v[0:1]
	global_store_dwordx2 v[94:95], v[92:93], off nt

.LBB0_485:
	v_or_b32_e32 v4, s41, v46
	v_lshlrev_b32_e32 v5, 1, v4
	v_and_b32_e32 v5, 0x7e0, v5
	v_or_b32_e32 v6, s40, v47
	s_waitcnt lgkmcnt(0)
	ds_read_b32 v90, v36 offset:224
	v_add_u32_e32 v5, v6, v5
	v_cndmask_b32_e64 v6, v4, v5, s[16:17]
	v_ashrrev_i32_e32 v4, 8, v6
	v_ashrrev_i32_e32 v5, 31, v4
	s_mov_b64 s[16:17], -1
	s_and_b64 vcc, exec, s[0:1]
	v_lshlrev_b32_sdwa v6, v211, v6 dst_sel:DWORD dst_unused:UNUSED_PAD src0_sel:DWORD src1_sel:BYTE_0
	s_cbranch_vccnz .LBB0_487
	ds_read2_b32 v[92:93], v36 offset0:121 offset1:186
	ds_read2_b32 v[94:95], v89 offset0:123 offset1:188
	ds_read2_b32 v[96:97], v88 offset0:125 offset1:190
	s_waitcnt lgkmcnt(3)
	v_mul_f32_e32 v7, 0x42800000, v90
	s_mov_b64 s[16:17], 0
	s_waitcnt lgkmcnt(2)
	v_mul_f32_e32 v91, 0x42800000, v92
	v_mov_b32_e32 v92, v33
	v_cvt_pk_fp8_f32 v92, v7, v91
	s_waitcnt lgkmcnt(1)
	v_mul_f32_e32 v7, 0x42800000, v95
	ds_read_b32 v95, v36 offset:2044
	v_mul_f32_e32 v98, 0x42800000, v93
	s_waitcnt lgkmcnt(1)
	v_mul_f32_e32 v91, 0x42800000, v96
	v_mov_b32_e32 v93, v33
	v_cvt_pk_fp8_f32 v93, v7, v91
	v_mul_f32_e32 v94, 0x42800000, v94
	v_cvt_pk_fp8_f32 v92, v98, v94 op_sel:[0,0,1]
	v_mul_f32_e32 v7, 0x42800000, v97
	s_waitcnt lgkmcnt(0)
	v_mul_f32_e32 v91, 0x42800000, v95
	v_lshlrev_b64 v[94:95], 18, v[4:5]
	v_cvt_pk_fp8_f32 v93, v7, v91 op_sel:[0,0,1]
	v_lshl_add_u64 v[94:95], s[26:27], 0, v[94:95]
	v_mov_b32_e32 v7, v33
	v_lshl_add_u64 v[94:95], v[94:95], 0, v[6:7]
	v_lshl_add_u64 v[94:95], v[94:95], 0, s[12:13]
	v_lshl_add_u64 v[94:95], v[94:95], 0, v[0:1]
	global_store_dwordx2 v[94:95], v[92:93], off nt
